# pre-pass column-max loop de-serialized: all 21(+1 guarded) row loads issued back-to-back, one wait, then max-reduce (was one load + vmcnt(0) per iteration)
# baseline (speedup 1.0000x reference)
; __device__ __forceinline__ void phase_colmax(const Params& p, LAS unsigned char* lds) {
;     ...
;     for (int blk = blockIdx.x; blk < 256; blk += gridDim.x) {
;         const int rg = blk >> 4, cb = blk & 15, col = 1024 + cb * 320 + cq * 4;
;         f32x4 m = (f32x4){0.f, 0.f, 0.f, 0.f};
;         if (sg < 6) for (int r = rg * 128 + sg; r < rg * 128 + 128; r += 6) { const f32x4 v = *(const f32x4*)(p.win + (size_t)r * NIN + col);
;             m[0] = fmaxf(m[0], fabsf(v[0])); m[1] = fmaxf(m[1], fabsf(v[1])); m[2] = fmaxf(m[2], fabsf(v[2])); m[3] = fmaxf(m[3], fabsf(v[3])); }
;         if (sg < 6) red[sg * 80 + cq] = m;
.LBB0_10:
	v_mov_b32_e32 v116, 0
	v_mov_b32_e32 v117, 0
	v_mov_b32_e32 v118, 0
	v_mov_b32_e32 v119, 0
	global_load_dwordx4 v[32:35], v[8:9], off
	v_lshl_add_u64 v[8:9], v[8:9], 0, s[6:7]
	global_load_dwordx4 v[36:39], v[8:9], off
	v_lshl_add_u64 v[8:9], v[8:9], 0, s[6:7]
	global_load_dwordx4 v[40:43], v[8:9], off
	v_lshl_add_u64 v[8:9], v[8:9], 0, s[6:7]
	global_load_dwordx4 v[44:47], v[8:9], off
	v_lshl_add_u64 v[8:9], v[8:9], 0, s[6:7]
	global_load_dwordx4 v[48:51], v[8:9], off
	v_lshl_add_u64 v[8:9], v[8:9], 0, s[6:7]
	global_load_dwordx4 v[52:55], v[8:9], off
	v_lshl_add_u64 v[8:9], v[8:9], 0, s[6:7]
	global_load_dwordx4 v[56:59], v[8:9], off
	v_lshl_add_u64 v[8:9], v[8:9], 0, s[6:7]
	global_load_dwordx4 v[60:63], v[8:9], off
	v_lshl_add_u64 v[8:9], v[8:9], 0, s[6:7]
	global_load_dwordx4 v[64:67], v[8:9], off
	v_lshl_add_u64 v[8:9], v[8:9], 0, s[6:7]
	global_load_dwordx4 v[68:71], v[8:9], off
	v_lshl_add_u64 v[8:9], v[8:9], 0, s[6:7]
	global_load_dwordx4 v[72:75], v[8:9], off
	v_lshl_add_u64 v[8:9], v[8:9], 0, s[6:7]
	global_load_dwordx4 v[76:79], v[8:9], off
	v_lshl_add_u64 v[8:9], v[8:9], 0, s[6:7]
	global_load_dwordx4 v[80:83], v[8:9], off
	v_lshl_add_u64 v[8:9], v[8:9], 0, s[6:7]
	global_load_dwordx4 v[84:87], v[8:9], off
	v_lshl_add_u64 v[8:9], v[8:9], 0, s[6:7]
	global_load_dwordx4 v[88:91], v[8:9], off
	v_lshl_add_u64 v[8:9], v[8:9], 0, s[6:7]
	global_load_dwordx4 v[92:95], v[8:9], off
	v_lshl_add_u64 v[8:9], v[8:9], 0, s[6:7]
	global_load_dwordx4 v[96:99], v[8:9], off
	v_lshl_add_u64 v[8:9], v[8:9], 0, s[6:7]
	global_load_dwordx4 v[100:103], v[8:9], off
	v_lshl_add_u64 v[8:9], v[8:9], 0, s[6:7]
	global_load_dwordx4 v[104:107], v[8:9], off
	v_lshl_add_u64 v[8:9], v[8:9], 0, s[6:7]
	global_load_dwordx4 v[108:111], v[8:9], off
	v_lshl_add_u64 v[8:9], v[8:9], 0, s[6:7]
	global_load_dwordx4 v[112:115], v[8:9], off
	v_lshl_add_u64 v[8:9], v[8:9], 0, s[6:7]
	v_cmp_gt_i32_e64 s[4:5], -4, v13
	s_nop 1
	s_and_saveexec_b64 s[52:53], s[4:5]
	global_load_dwordx4 v[116:119], v[8:9], off
	s_mov_b64 exec, s[52:53]
	s_waitcnt vmcnt(0)
	v_max_f32_e64 v2, v2, |v32|
	v_max_f32_e64 v3, v3, |v33|
	v_max_f32_e64 v4, v4, |v34|
	v_max_f32_e64 v5, v5, |v35|
	v_max_f32_e64 v2, v2, |v36|
	v_max_f32_e64 v3, v3, |v37|
	v_max_f32_e64 v4, v4, |v38|
	v_max_f32_e64 v5, v5, |v39|
	v_max_f32_e64 v2, v2, |v40|
	v_max_f32_e64 v3, v3, |v41|
	v_max_f32_e64 v4, v4, |v42|
	v_max_f32_e64 v5, v5, |v43|
	v_max_f32_e64 v2, v2, |v44|
	v_max_f32_e64 v3, v3, |v45|
	v_max_f32_e64 v4, v4, |v46|
	v_max_f32_e64 v5, v5, |v47|
	v_max_f32_e64 v2, v2, |v48|
	v_max_f32_e64 v3, v3, |v49|
	v_max_f32_e64 v4, v4, |v50|
	v_max_f32_e64 v5, v5, |v51|
	v_max_f32_e64 v2, v2, |v52|
	v_max_f32_e64 v3, v3, |v53|
	v_max_f32_e64 v4, v4, |v54|
	v_max_f32_e64 v5, v5, |v55|
	v_max_f32_e64 v2, v2, |v56|
	v_max_f32_e64 v3, v3, |v57|
	v_max_f32_e64 v4, v4, |v58|
	v_max_f32_e64 v5, v5, |v59|
	v_max_f32_e64 v2, v2, |v60|
	v_max_f32_e64 v3, v3, |v61|
	v_max_f32_e64 v4, v4, |v62|
	v_max_f32_e64 v5, v5, |v63|
	v_max_f32_e64 v2, v2, |v64|
	v_max_f32_e64 v3, v3, |v65|
	v_max_f32_e64 v4, v4, |v66|
	v_max_f32_e64 v5, v5, |v67|
	v_max_f32_e64 v2, v2, |v68|
	v_max_f32_e64 v3, v3, |v69|
	v_max_f32_e64 v4, v4, |v70|
	v_max_f32_e64 v5, v5, |v71|
	v_max_f32_e64 v2, v2, |v72|
	v_max_f32_e64 v3, v3, |v73|
	v_max_f32_e64 v4, v4, |v74|
	v_max_f32_e64 v5, v5, |v75|
	v_max_f32_e64 v2, v2, |v76|
	v_max_f32_e64 v3, v3, |v77|
	v_max_f32_e64 v4, v4, |v78|
	v_max_f32_e64 v5, v5, |v79|
	v_max_f32_e64 v2, v2, |v80|
	v_max_f32_e64 v3, v3, |v81|
	v_max_f32_e64 v4, v4, |v82|
	v_max_f32_e64 v5, v5, |v83|
	v_max_f32_e64 v2, v2, |v84|
	v_max_f32_e64 v3, v3, |v85|
	v_max_f32_e64 v4, v4, |v86|
	v_max_f32_e64 v5, v5, |v87|
	v_max_f32_e64 v2, v2, |v88|
	v_max_f32_e64 v3, v3, |v89|
	v_max_f32_e64 v4, v4, |v90|
	v_max_f32_e64 v5, v5, |v91|
	v_max_f32_e64 v2, v2, |v92|
	v_max_f32_e64 v3, v3, |v93|
	v_max_f32_e64 v4, v4, |v94|
	v_max_f32_e64 v5, v5, |v95|
	v_max_f32_e64 v2, v2, |v96|
	v_max_f32_e64 v3, v3, |v97|
	v_max_f32_e64 v4, v4, |v98|
	v_max_f32_e64 v5, v5, |v99|
	v_max_f32_e64 v2, v2, |v100|
	v_max_f32_e64 v3, v3, |v101|
	v_max_f32_e64 v4, v4, |v102|
	v_max_f32_e64 v5, v5, |v103|
	v_max_f32_e64 v2, v2, |v104|
	v_max_f32_e64 v3, v3, |v105|
	v_max_f32_e64 v4, v4, |v106|
	v_max_f32_e64 v5, v5, |v107|
	v_max_f32_e64 v2, v2, |v108|
	v_max_f32_e64 v3, v3, |v109|
	v_max_f32_e64 v4, v4, |v110|
	v_max_f32_e64 v5, v5, |v111|
	v_max_f32_e64 v2, v2, |v112|
	v_max_f32_e64 v3, v3, |v113|
	v_max_f32_e64 v4, v4, |v114|
	v_max_f32_e64 v5, v5, |v115|
	v_max_f32_e64 v2, v2, |v116|
	v_max_f32_e64 v3, v3, |v117|
	v_max_f32_e64 v4, v4, |v118|
	v_max_f32_e64 v5, v5, |v119|
	s_mov_b64 s[52:53], exec
	s_or_b64 exec, exec, s[52:53]
